# prologue: weight transposes dealt in two stages so the workgroups that also compute the modulation tables get a smaller share (balanced finish)
# speedup vs baseline: 1.0022x; 1.0022x over previous
; #define LAS __attribute__((address_space(3)))
; __device__ __forceinline__ void phase_prologue(const Params& p, LAS unsigned char* lds, int G, int tid, int wave, int lane) {
;     ...
;     LAS float* scr = (LAS float*)(lds + wave * 16384);
;     const int gw = blockIdx.x * NWAVES + wave, NGW = G * NWAVES;
;     constexpr int I_IN = 16 * 64, I_O = 8 * 32, I_1 = 16 * 128, I_2 = 64 * 32, I_L = I_IN + I_O + I_1 + I_2;
;     for (int it = gw; it < DEPTH * I_L; it += NGW) {
;         const int l = it / I_L; int r = it % I_L;
;         if (r < I_IN) { transpose_item(p.in[I_WIN] + (size_t)l * DM * NIN, NIN, (bf16_t*)(p.ws + WS_WIN) + (size_t)l * NIN * DM, DM, 0, NIN / 32, scr, r, lane); continue; } r -= I_IN;
;         if (r < I_O) { transpose_item(p.in[I_WOUT] + (size_t)l * DM * DM + (size_t)512 * DM, DM, (bf16_t*)(p.ws + WS_WOUT) + (size_t)l * DM * DM, DM, 512, DM / 32, scr, r, lane); continue; } r -= I_O;
;         if (r < I_1) { transpose_item(p.in[I_W1] + (size_t)l * DM * FF, FF, (bf16_t*)(p.ws + WS_W1) + (size_t)l * FF * DM, DM, 0, FF / 32, scr, r, lane); continue; } r -= I_1;
;         transpose_item(p.in[I_W2] + (size_t)l * FF * DM, DM, (bf16_t*)(p.ws + WS_W2) + (size_t)l * DM * FF, FF, 0, DM / 32, scr, r, lane);
;     }
.LBB0_401:
	v_readlane_b32 s0, v254, 22
	s_add_i32 s10, s87, s0
	s_mov_b32 s32, s52
	s_cmpk_lg_u32 s52, 0x800
	s_cbranch_scc1 .Ltr_std
	s_cmpk_lt_i32 s10, 0x300
	s_cbranch_scc1 .Ltr_lo
	s_sub_i32 s10, s10, 0x300
	s_movk_i32 s32, 0x500
	s_branch .Ltr_std
.Ltr_lo:
	s_add_i32 s10, s10, 0x2800

; __device__ __forceinline__ void phase_prologue(const Params& p, LAS unsigned char* lds, int G, int tid, int wave, int lane) {
;     ...
;     for (int it = gw; it < DEPTH * I_L; it += NGW) {
;         const int l = it / I_L; int r = it % I_L;
;         if (r < I_IN) { transpose_item(p.in[I_WIN] + (size_t)l * DM * NIN, NIN, (bf16_t*)(p.ws + WS_WIN) + (size_t)l * NIN * DM, DM, 0, NIN / 32, scr, r, lane); continue; } r -= I_IN;
;         if (r < I_O) { transpose_item(p.in[I_WOUT] + (size_t)l * DM * DM + (size_t)512 * DM, DM, (bf16_t*)(p.ws + WS_WOUT) + (size_t)l * DM * DM, DM, 512, DM / 32, scr, r, lane); continue; } r -= I_O;
;         if (r < I_1) { transpose_item(p.in[I_W1] + (size_t)l * DM * FF, FF, (bf16_t*)(p.ws + WS_W1) + (size_t)l * FF * DM, DM, 0, FF / 32, scr, r, lane); continue; } r -= I_1;
;         transpose_item(p.in[I_W2] + (size_t)l * FF * DM, DM, (bf16_t*)(p.ws + WS_W2) + (size_t)l * DM * FF, FF, 0, DM / 32, scr, r, lane);
;     }
.LBB0_403:
	s_add_i32 s10, s10, s32
	s_cmpk_lg_u32 s32, 0x500
	s_cbranch_scc1 .Ltr_chk
	s_cmpk_lt_i32 s10, 0x2800
	s_cbranch_scc1 .LBB0_404
	s_mov_b32 s32, s52
	v_readlane_b32 s0, v254, 22
	s_nop 0
	s_add_i32 s10, s87, s0
	s_add_i32 s10, s10, 0x2800
.Ltr_chk:
	s_cmpk_gt_i32 s10, 0x53ff
	s_cbranch_scc1 .LBB0_424
.LBB0_404:
	s_mul_hi_i32 s0, s10, 0x30c30c31
	s_lshr_b32 s1, s0, 31
	s_ashr_i32 s0, s0, 10
	s_add_i32 s0, s0, s1
	s_mul_i32 s1, s0, 0x1500
	s_sub_i32 s23, s10, s1
	s_ashr_i32 s1, s0, 31
	s_cmpk_gt_i32 s23, 0x3ff
	s_mov_b64 s[4:5], -1
	s_cbranch_scc1 .LBB0_406
	s_andn2_b64 vcc, exec, s[4:5]
	s_cbranch_vccnz .LBB0_403
	s_branch .LBB0_421
